# attention softmax fast path: exps first, row sum doubles as the rescale trigger (lane sum <= 256 implies every score <= 8), max tree only on the rare path
# baseline (speedup 1.0000x reference)
.LBB0_227:
	s_lshl_b32 s4, s59, 11
	s_and_b32 s5, s4, 0x1000000
	s_lshl_b32 s4, s36, 4
	s_and_b32 s28, s4, 0x700
	v_lshl_or_b32 v96, v148, 1, s28
	v_or_b32_e32 v96, s5, v96
	v_mov_b32_e32 v97, v209
	s_lshl_b32 s21, s21, 9
	s_mov_b32 s65, 2
	s_add_i32 s66, s8, 2
	s_mov_b32 s4, 1
	v_lshl_add_u64 v[174:175], v[170:171], 0, v[96:97]
	v_subrev_u32_e32 v204, s21, v194
	s_add_i32 s33, s61, s8
	s_mov_b32 s87, 0
	s_movk_i32 s68, 0xff00
	s_waitcnt lgkmcnt(0)
	s_barrier
	s_and_b64 vcc, exec, s[16:17]
	s_cbranch_vccnz .LBB0_228
	s_cmp_lt_i32 s9, 1
	s_cbranch_scc1 .LBB0_228
	s_movk_i32 s5, 0x4400
	v_add_u32_e32 v205, s5, v192
	ds_read_b128 v[96:99], v205 offset:8704
	ds_read_b128 v[100:103], v205 offset:8736
	ds_read_b128 v[104:107], v205 offset:8768
	ds_read_b128 v[108:111], v205 offset:8800
	ds_read_b128 v[176:179], v205
	ds_read_b128 v[180:183], v205 offset:32
	ds_read_b128 v[184:187], v205 offset:64
	ds_read_b128 v[188:191], v205 offset:96
	s_waitcnt lgkmcnt(7)
	v_mfma_f32_32x32x16_bf16 v[80:95], v[96:99], v[112:115], v[64:79]
	s_waitcnt lgkmcnt(6)
	v_mfma_f32_32x32x16_bf16 v[80:95], v[100:103], v[116:119], v[80:95]
	s_waitcnt lgkmcnt(5)
	v_mfma_f32_32x32x16_bf16 v[80:95], v[104:107], v[120:123], v[80:95]
	s_waitcnt lgkmcnt(4)
	v_mfma_f32_32x32x16_bf16 v[80:95], v[108:111], v[124:127], v[80:95]
	s_waitcnt lgkmcnt(3)
	v_mfma_f32_32x32x16_bf16 v[96:111], v[176:179], v[112:115], v[64:79]
	s_waitcnt lgkmcnt(2)
	v_mfma_f32_32x32x16_bf16 v[96:111], v[180:183], v[116:119], v[96:111]
	s_waitcnt lgkmcnt(1)
	v_mfma_f32_32x32x16_bf16 v[96:111], v[184:187], v[120:123], v[96:111]
	s_waitcnt lgkmcnt(0)
	v_mfma_f32_32x32x16_bf16 v[96:111], v[188:191], v[124:127], v[96:111]
	s_cmp_gt_i32 s33, 2
	s_cbranch_scc1 .LBB0_228
	s_waitcnt lgkmcnt(0)
	v_subrev_u32_e32 v204, s21, v194
	v_add_u32_e32 v205, s68, v204
	v_add_u32_e32 v176, 0x17d00, v205
	v_add_u32_e32 v178, 0x17d80, v205
	ds_read2_b32 v[176:177], v176 offset1:1
	ds_read2_b32 v[178:179], v178 offset1:1
	v_add_u32_e32 v180, 0x17d08, v205
	v_add_u32_e32 v182, 0x17d88, v205
	v_add_u32_e32 v184, 0x17d20, v205
	v_add_u32_e32 v186, 0x17da0, v205
	v_add_u32_e32 v188, 0x17d28, v205
	v_add_u32_e32 v190, 0x17da8, v205
	v_add_u32_e32 v206, 0x17d40, v205
	v_add_u32_e32 v210, 0x17dc0, v205
	v_add_u32_e32 v212, 0x17d48, v205
	v_add_u32_e32 v221, 0x17dc8, v205
	ds_read2_b32 v[180:181], v180 offset1:1
	ds_read2_b32 v[182:183], v182 offset1:1
	ds_read2_b32 v[184:185], v184 offset1:1
	ds_read2_b32 v[186:187], v186 offset1:1
	ds_read2_b32 v[188:189], v188 offset1:1
	ds_read2_b32 v[190:191], v190 offset1:1
	ds_read2_b32 v[206:207], v206 offset1:1
	ds_read2_b32 v[210:211], v210 offset1:1
	ds_read2_b32 v[212:213], v212 offset1:1
	ds_read2_b32 v[224:225], v221 offset1:1
	v_add_u32_e32 v221, 0x17d60, v205
	v_add_u32_e32 v223, 0x17de0, v205
	ds_read2_b32 v[226:227], v221 offset1:1
	ds_read2_b32 v[228:229], v223 offset1:1
	v_add_u32_e32 v221, 0x17d68, v205
	v_add_u32_e32 v205, 0x17de8, v205
	ds_read2_b32 v[230:231], v221 offset1:1
	s_waitcnt lgkmcnt(14)
	v_pk_add_f32 v[96:97], v[96:97], v[176:177]
	ds_read2_b32 v[176:177], v205 offset1:1
	s_waitcnt lgkmcnt(3)
	v_pk_add_f32 v[108:109], v[108:109], v[226:227]
	v_pk_add_f32 v[106:107], v[106:107], v[212:213]
	s_waitcnt lgkmcnt(1)
	v_pk_add_f32 v[110:111], v[110:111], v[230:231]
	v_pk_add_f32 v[104:105], v[104:105], v[206:207]
	v_pk_add_f32 v[102:103], v[102:103], v[188:189]
	v_pk_add_f32 v[100:101], v[100:101], v[184:185]
	v_pk_add_f32 v[98:99], v[98:99], v[180:181]
	s_waitcnt lgkmcnt(0)
	v_pk_add_f32 v[94:95], v[94:95], v[176:177]
	v_pk_add_f32 v[92:93], v[92:93], v[228:229]
	v_pk_add_f32 v[90:91], v[90:91], v[224:225]
	v_pk_add_f32 v[88:89], v[88:89], v[210:211]
	v_pk_add_f32 v[86:87], v[86:87], v[190:191]
	v_pk_add_f32 v[84:85], v[84:85], v[186:187]
	v_pk_add_f32 v[82:83], v[82:83], v[182:183]
	v_pk_add_f32 v[80:81], v[80:81], v[178:179]
	s_nop 0

.Latt_b_sm:
	s_cmp_gt_i32 s86, s9
	s_cbranch_scc1 .Latt_b_bar
	v_exp_f32_e32 v224, v96
	v_exp_f32_e32 v225, v97
	v_exp_f32_e32 v176, v80
	v_exp_f32_e32 v177, v81
	v_exp_f32_e32 v226, v98
	v_exp_f32_e32 v227, v99
	v_exp_f32_e32 v178, v82
	v_exp_f32_e32 v179, v83
	v_exp_f32_e32 v228, v100
	v_exp_f32_e32 v229, v101
	v_exp_f32_e32 v180, v84
	v_exp_f32_e32 v181, v85
	v_exp_f32_e32 v230, v102
	v_exp_f32_e32 v231, v103
	v_exp_f32_e32 v182, v86
	v_exp_f32_e32 v183, v87
	v_exp_f32_e32 v248, v104
	v_exp_f32_e32 v249, v105
	v_exp_f32_e32 v184, v88
	v_exp_f32_e32 v185, v89
	v_exp_f32_e32 v250, v106
	v_exp_f32_e32 v251, v107
	v_exp_f32_e32 v186, v90
	v_exp_f32_e32 v187, v91
	v_exp_f32_e32 v210, v108
	v_exp_f32_e32 v211, v109
	v_exp_f32_e32 v188, v92
	v_exp_f32_e32 v189, v93
	v_exp_f32_e32 v212, v110
	v_exp_f32_e32 v213, v111
	v_exp_f32_e32 v190, v94
	v_exp_f32_e32 v191, v95
	v_pk_add_f32 v[204:205], v[224:225], v[226:227]
	v_pk_add_f32 v[206:207], v[210:211], v[212:213]
	v_pk_add_f32 v[232:233], v[182:183], v[184:185]
	v_pk_add_f32 v[204:205], v[204:205], v[228:229]
	v_pk_add_f32 v[206:207], v[206:207], v[176:177]
	v_pk_add_f32 v[232:233], v[232:233], v[186:187]
	v_pk_add_f32 v[204:205], v[204:205], v[230:231]
	v_pk_add_f32 v[206:207], v[206:207], v[178:179]
	v_pk_add_f32 v[232:233], v[232:233], v[188:189]
	v_pk_add_f32 v[204:205], v[204:205], v[248:249]
	v_pk_add_f32 v[206:207], v[206:207], v[180:181]
	v_pk_add_f32 v[232:233], v[232:233], v[190:191]
	v_pk_add_f32 v[204:205], v[204:205], v[250:251]
	s_nop 0
	v_pk_add_f32 v[204:205], v[204:205], v[206:207]
	s_nop 0
	v_pk_add_f32 v[204:205], v[204:205], v[232:233]
	s_nop 0
	v_add_f32_e32 v204, v204, v205
	v_cmp_nge_f32_e32 vcc, 0x43800000, v204
	s_cbranch_vccnz .Latt_b_rare
	v_cvt_pk_bf16_f32 v80, v224, v225
	v_cvt_pk_bf16_f32 v81, v226, v227
	v_cvt_pk_bf16_f32 v82, v228, v229
	v_cvt_pk_bf16_f32 v83, v230, v231
	v_cvt_pk_bf16_f32 v84, v248, v249
	v_cvt_pk_bf16_f32 v85, v250, v251
	v_cvt_pk_bf16_f32 v86, v210, v211
	v_cvt_pk_bf16_f32 v87, v212, v213
	v_cvt_pk_bf16_f32 v88, v176, v177
	v_cvt_pk_bf16_f32 v89, v178, v179
	v_cvt_pk_bf16_f32 v90, v180, v181
	v_cvt_pk_bf16_f32 v91, v182, v183
	v_cvt_pk_bf16_f32 v92, v184, v185
	v_cvt_pk_bf16_f32 v93, v186, v187
	v_cvt_pk_bf16_f32 v94, v188, v189
	v_cvt_pk_bf16_f32 v95, v190, v191
	v_add_f32_e32 v172, v172, v204
.Latt_b_smdone:
.Latt_b_bar:
	s_waitcnt lgkmcnt(0)
	s_barrier
	s_cmp_gt_i32 s86, s9
	s_cbranch_scc1 .LBB0_241
	s_cmp_ge_i32 s86, s9
	s_cbranch_scc1 .Latt_b_pvonly
	s_mul_i32 s4, s69, 0x5000
	v_add_u32_e32 v205, s4, v165
	v_add_u32_e32 v206, s28, v192
	ds_read_b64_tr_b16 v[96:97], v205 offset:34816
	ds_read_b64_tr_b16 v[98:99], v205 offset:37376
	ds_read_b64_tr_b16 v[100:101], v205 offset:39936
	ds_read_b64_tr_b16 v[102:103], v205 offset:42496
	ds_read_b64_tr_b16 v[104:105], v205 offset:45056
	ds_read_b64_tr_b16 v[106:107], v205 offset:47616
	ds_read_b64_tr_b16 v[108:109], v205 offset:50176
	ds_read_b64_tr_b16 v[110:111], v205 offset:52736
	ds_read_b64_tr_b16 v[176:177], v205 offset:34880
	ds_read_b64_tr_b16 v[178:179], v205 offset:37440
	ds_read_b64_tr_b16 v[180:181], v205 offset:40000
	ds_read_b64_tr_b16 v[182:183], v205 offset:42560
	ds_read_b64_tr_b16 v[184:185], v205 offset:45120
	ds_read_b64_tr_b16 v[186:187], v205 offset:47680
	s_setprio 1
	s_waitcnt lgkmcnt(12)
	v_mfma_f32_32x32x16_bf16 v[32:47], v[96:99], v[80:83], v[32:47]
	ds_read_b64_tr_b16 v[96:97], v205 offset:50240
	ds_read_b64_tr_b16 v[98:99], v205 offset:52800
	s_waitcnt lgkmcnt(12)
	v_mfma_f32_32x32x16_bf16 v[32:47], v[100:103], v[84:87], v[32:47]
	ds_read_b64_tr_b16 v[100:101], v205 offset:34944
	ds_read_b64_tr_b16 v[102:103], v205 offset:37504
	s_waitcnt lgkmcnt(12)
	v_mfma_f32_32x32x16_bf16 v[32:47], v[104:107], v[88:91], v[32:47]
	ds_read_b64_tr_b16 v[104:105], v205 offset:40064
	ds_read_b64_tr_b16 v[106:107], v205 offset:42624
	s_waitcnt lgkmcnt(12)
	v_mfma_f32_32x32x16_bf16 v[32:47], v[108:111], v[92:95], v[32:47]
	ds_read_b64_tr_b16 v[108:109], v205 offset:45184
	ds_read_b64_tr_b16 v[110:111], v205 offset:47744
	s_waitcnt lgkmcnt(12)
	v_mfma_f32_32x32x16_bf16 v[16:31], v[176:179], v[80:83], v[16:31]
	ds_read_b64_tr_b16 v[176:177], v205 offset:50304
	ds_read_b64_tr_b16 v[178:179], v205 offset:52864
	s_waitcnt lgkmcnt(12)
	v_mfma_f32_32x32x16_bf16 v[16:31], v[180:183], v[84:87], v[16:31]
	ds_read_b64_tr_b16 v[180:181], v205 offset:35008
	ds_read_b64_tr_b16 v[182:183], v205 offset:37568
	s_waitcnt lgkmcnt(12)
	v_mfma_f32_32x32x16_bf16 v[16:31], v[184:187], v[88:91], v[16:31]
	ds_read_b64_tr_b16 v[184:185], v205 offset:40128
	ds_read_b64_tr_b16 v[186:187], v205 offset:42688
	s_waitcnt lgkmcnt(12)
	v_mfma_f32_32x32x16_bf16 v[16:31], v[96:99], v[92:95], v[16:31]
	ds_read_b64_tr_b16 v[96:97], v205 offset:45248
	ds_read_b64_tr_b16 v[98:99], v205 offset:47808
	s_waitcnt lgkmcnt(12)
	v_mfma_f32_32x32x16_bf16 v[0:15], v[100:103], v[80:83], v[0:15]
	ds_read_b64_tr_b16 v[100:101], v205 offset:50368
	ds_read_b64_tr_b16 v[102:103], v205 offset:52928
	s_waitcnt lgkmcnt(12)
	v_mfma_f32_32x32x16_bf16 v[0:15], v[104:107], v[84:87], v[0:15]
	ds_read_b128 v[210:213], v206 offset:8704
	ds_read_b128 v[104:107], v206 offset:8736
	s_waitcnt lgkmcnt(12)
	v_mfma_f32_32x32x16_bf16 v[0:15], v[108:111], v[88:91], v[0:15]
	ds_read_b128 v[108:111], v206 offset:8768
	ds_read_b128 v[188:191], v206
	s_waitcnt lgkmcnt(12)
	v_mfma_f32_32x32x16_bf16 v[0:15], v[176:179], v[92:95], v[0:15]
	ds_read_b128 v[176:179], v206 offset:8800
	ds_read_b128 v[224:227], v206 offset:32
	s_waitcnt lgkmcnt(12)
	v_mfma_f32_32x32x16_bf16 v[48:63], v[180:183], v[80:83], v[48:63]
	ds_read_b128 v[228:231], v206 offset:64
	ds_read_b128 v[248:251], v206 offset:96
	s_waitcnt lgkmcnt(12)
	v_mfma_f32_32x32x16_bf16 v[48:63], v[184:187], v[84:87], v[48:63]
	s_waitcnt lgkmcnt(10)
	v_mfma_f32_32x32x16_bf16 v[48:63], v[96:99], v[88:91], v[48:63]
	s_waitcnt lgkmcnt(8)
	v_mfma_f32_32x32x16_bf16 v[48:63], v[100:103], v[92:95], v[48:63]
	s_waitcnt lgkmcnt(3)
	v_mfma_f32_32x32x16_bf16 v[80:95], v[210:213], v[112:115], v[64:79]
	v_mfma_f32_32x32x16_bf16 v[80:95], v[104:107], v[116:119], v[80:95]
	v_mfma_f32_32x32x16_bf16 v[80:95], v[108:111], v[120:123], v[80:95]
	v_mfma_f32_32x32x16_bf16 v[80:95], v[176:179], v[124:127], v[80:95]
	s_waitcnt lgkmcnt(0)
	v_mfma_f32_32x32x16_bf16 v[96:111], v[188:191], v[112:115], v[64:79]
	v_mfma_f32_32x32x16_bf16 v[96:111], v[224:227], v[116:119], v[96:111]
	v_mfma_f32_32x32x16_bf16 v[96:111], v[228:231], v[120:123], v[96:111]
	v_mfma_f32_32x32x16_bf16 v[96:111], v[248:251], v[124:127], v[96:111]
	s_setprio 0
	s_cmp_gt_i32 s33, 3
	s_cbranch_scc1 .LBB0_241
	s_waitcnt lgkmcnt(0)
	s_add_i32 s4, s68, 0x100
	v_subrev_u32_e32 v204, s21, v194
	v_add_u32_e32 v205, s4, v204
	v_add_u32_e32 v176, 0x17d00, v205
	v_add_u32_e32 v178, 0x17d80, v205
	ds_read2_b32 v[176:177], v176 offset1:1
	ds_read2_b32 v[178:179], v178 offset1:1
	v_add_u32_e32 v180, 0x17d08, v205
	v_add_u32_e32 v182, 0x17d88, v205
	v_add_u32_e32 v184, 0x17d20, v205
	v_add_u32_e32 v186, 0x17da0, v205
	v_add_u32_e32 v188, 0x17d28, v205
	v_add_u32_e32 v190, 0x17da8, v205
	v_add_u32_e32 v206, 0x17d40, v205
	v_add_u32_e32 v210, 0x17dc0, v205
	v_add_u32_e32 v212, 0x17d48, v205
	v_add_u32_e32 v221, 0x17dc8, v205
	ds_read2_b32 v[180:181], v180 offset1:1
	ds_read2_b32 v[182:183], v182 offset1:1
	ds_read2_b32 v[184:185], v184 offset1:1
	ds_read2_b32 v[186:187], v186 offset1:1
	ds_read2_b32 v[188:189], v188 offset1:1
	ds_read2_b32 v[190:191], v190 offset1:1
	ds_read2_b32 v[206:207], v206 offset1:1
	ds_read2_b32 v[210:211], v210 offset1:1
	ds_read2_b32 v[212:213], v212 offset1:1
	ds_read2_b32 v[224:225], v221 offset1:1
	v_add_u32_e32 v221, 0x17d60, v205
	v_add_u32_e32 v223, 0x17de0, v205
	ds_read2_b32 v[226:227], v221 offset1:1
	ds_read2_b32 v[228:229], v223 offset1:1
	v_add_u32_e32 v221, 0x17d68, v205
	v_add_u32_e32 v205, 0x17de8, v205
	ds_read2_b32 v[230:231], v221 offset1:1
	s_waitcnt lgkmcnt(14)
	v_pk_add_f32 v[96:97], v[96:97], v[176:177]
	ds_read2_b32 v[176:177], v205 offset1:1
	s_waitcnt lgkmcnt(3)
	v_pk_add_f32 v[108:109], v[108:109], v[226:227]
	v_pk_add_f32 v[106:107], v[106:107], v[212:213]
	s_waitcnt lgkmcnt(1)
	v_pk_add_f32 v[110:111], v[110:111], v[230:231]
	v_pk_add_f32 v[104:105], v[104:105], v[206:207]
	v_pk_add_f32 v[102:103], v[102:103], v[188:189]
	v_pk_add_f32 v[100:101], v[100:101], v[184:185]
	v_pk_add_f32 v[98:99], v[98:99], v[180:181]
	s_waitcnt lgkmcnt(0)
	v_pk_add_f32 v[94:95], v[94:95], v[176:177]
	v_pk_add_f32 v[92:93], v[92:93], v[228:229]
	v_pk_add_f32 v[90:91], v[90:91], v[224:225]
	v_pk_add_f32 v[88:89], v[88:89], v[210:211]
	v_pk_add_f32 v[86:87], v[86:87], v[190:191]
	v_pk_add_f32 v[84:85], v[84:85], v[186:187]
	v_pk_add_f32 v[82:83], v[82:83], v[182:183]
	v_pk_add_f32 v[80:81], v[80:81], v[178:179]
	s_nop 0
	s_branch .LBB0_241

.Latt_a:
	s_mul_i32 s4, s87, 0x5000
	v_add_u32_e32 v205, s4, v165
	v_add_u32_e32 v206, s5, v192
	ds_read_b64_tr_b16 v[96:97], v205 offset:34816
	ds_read_b64_tr_b16 v[98:99], v205 offset:37376
	ds_read_b64_tr_b16 v[100:101], v205 offset:39936
	ds_read_b64_tr_b16 v[102:103], v205 offset:42496
	ds_read_b64_tr_b16 v[104:105], v205 offset:45056
	ds_read_b64_tr_b16 v[106:107], v205 offset:47616
	ds_read_b64_tr_b16 v[108:109], v205 offset:50176
	ds_read_b64_tr_b16 v[110:111], v205 offset:52736
	ds_read_b64_tr_b16 v[176:177], v205 offset:34880
	ds_read_b64_tr_b16 v[178:179], v205 offset:37440
	ds_read_b64_tr_b16 v[180:181], v205 offset:40000
	ds_read_b64_tr_b16 v[182:183], v205 offset:42560
	ds_read_b64_tr_b16 v[184:185], v205 offset:45120
	ds_read_b64_tr_b16 v[186:187], v205 offset:47680
	s_setprio 1
	s_waitcnt lgkmcnt(12)
	v_mfma_f32_32x32x16_bf16 v[32:47], v[96:99], v[80:83], v[32:47]
	ds_read_b64_tr_b16 v[96:97], v205 offset:50240
	ds_read_b64_tr_b16 v[98:99], v205 offset:52800
	s_waitcnt lgkmcnt(12)
	v_mfma_f32_32x32x16_bf16 v[32:47], v[100:103], v[84:87], v[32:47]
	ds_read_b64_tr_b16 v[100:101], v205 offset:34944
	ds_read_b64_tr_b16 v[102:103], v205 offset:37504
	s_waitcnt lgkmcnt(12)
	v_mfma_f32_32x32x16_bf16 v[32:47], v[104:107], v[88:91], v[32:47]
	ds_read_b64_tr_b16 v[104:105], v205 offset:40064
	ds_read_b64_tr_b16 v[106:107], v205 offset:42624
	s_waitcnt lgkmcnt(12)
	v_mfma_f32_32x32x16_bf16 v[32:47], v[108:111], v[92:95], v[32:47]
	ds_read_b64_tr_b16 v[108:109], v205 offset:45184
	ds_read_b64_tr_b16 v[110:111], v205 offset:47744
	s_waitcnt lgkmcnt(12)
	v_mfma_f32_32x32x16_bf16 v[16:31], v[176:179], v[80:83], v[16:31]
	ds_read_b64_tr_b16 v[176:177], v205 offset:50304
	ds_read_b64_tr_b16 v[178:179], v205 offset:52864
	s_waitcnt lgkmcnt(12)
	v_mfma_f32_32x32x16_bf16 v[16:31], v[180:183], v[84:87], v[16:31]
	ds_read_b64_tr_b16 v[180:181], v205 offset:35008
	ds_read_b64_tr_b16 v[182:183], v205 offset:37568
	s_waitcnt lgkmcnt(12)
	v_mfma_f32_32x32x16_bf16 v[16:31], v[184:187], v[88:91], v[16:31]
	ds_read_b64_tr_b16 v[184:185], v205 offset:40128
	ds_read_b64_tr_b16 v[186:187], v205 offset:42688
	s_waitcnt lgkmcnt(12)
	v_mfma_f32_32x32x16_bf16 v[16:31], v[96:99], v[92:95], v[16:31]
	ds_read_b64_tr_b16 v[96:97], v205 offset:45248
	ds_read_b64_tr_b16 v[98:99], v205 offset:47808
	s_waitcnt lgkmcnt(12)
	v_mfma_f32_32x32x16_bf16 v[0:15], v[100:103], v[80:83], v[0:15]
	ds_read_b64_tr_b16 v[100:101], v205 offset:50368
	ds_read_b64_tr_b16 v[102:103], v205 offset:52928
	s_waitcnt lgkmcnt(12)
	v_mfma_f32_32x32x16_bf16 v[0:15], v[104:107], v[84:87], v[0:15]
	ds_read_b128 v[210:213], v206 offset:8704
	ds_read_b128 v[104:107], v206 offset:8736
	s_waitcnt lgkmcnt(12)
	v_mfma_f32_32x32x16_bf16 v[0:15], v[108:111], v[88:91], v[0:15]
	ds_read_b128 v[108:111], v206 offset:8768
	ds_read_b128 v[188:191], v206
	s_waitcnt lgkmcnt(12)
	v_mfma_f32_32x32x16_bf16 v[0:15], v[176:179], v[92:95], v[0:15]
	ds_read_b128 v[176:179], v206 offset:8800
	ds_read_b128 v[224:227], v206 offset:32
	s_waitcnt lgkmcnt(12)
	v_mfma_f32_32x32x16_bf16 v[48:63], v[180:183], v[80:83], v[48:63]
	ds_read_b128 v[228:231], v206 offset:64
	ds_read_b128 v[248:251], v206 offset:96
	s_waitcnt lgkmcnt(12)
	v_mfma_f32_32x32x16_bf16 v[48:63], v[184:187], v[84:87], v[48:63]
	s_waitcnt lgkmcnt(10)
	v_mfma_f32_32x32x16_bf16 v[48:63], v[96:99], v[88:91], v[48:63]
	s_waitcnt lgkmcnt(8)
	v_mfma_f32_32x32x16_bf16 v[48:63], v[100:103], v[92:95], v[48:63]
	s_waitcnt lgkmcnt(3)
	v_mfma_f32_32x32x16_bf16 v[80:95], v[210:213], v[112:115], v[64:79]
	v_mfma_f32_32x32x16_bf16 v[80:95], v[104:107], v[116:119], v[80:95]
	v_mfma_f32_32x32x16_bf16 v[80:95], v[108:111], v[120:123], v[80:95]
	v_mfma_f32_32x32x16_bf16 v[80:95], v[176:179], v[124:127], v[80:95]
	s_waitcnt lgkmcnt(0)
	v_mfma_f32_32x32x16_bf16 v[96:111], v[188:191], v[112:115], v[64:79]
	v_mfma_f32_32x32x16_bf16 v[96:111], v[224:227], v[116:119], v[96:111]
	v_mfma_f32_32x32x16_bf16 v[96:111], v[228:231], v[120:123], v[96:111]
	v_mfma_f32_32x32x16_bf16 v[96:111], v[248:251], v[124:127], v[96:111]
	s_setprio 0
	s_cmp_gt_i32 s33, 2
	s_cbranch_scc1 .Latt_a_stg
	s_waitcnt lgkmcnt(0)
	v_subrev_u32_e32 v204, s21, v194
	v_add_u32_e32 v205, s68, v204
	v_add_u32_e32 v176, 0x17d00, v205
	v_add_u32_e32 v178, 0x17d80, v205
	ds_read2_b32 v[176:177], v176 offset1:1
	ds_read2_b32 v[178:179], v178 offset1:1
	v_add_u32_e32 v180, 0x17d08, v205
	v_add_u32_e32 v182, 0x17d88, v205
	v_add_u32_e32 v184, 0x17d20, v205
	v_add_u32_e32 v186, 0x17da0, v205
	v_add_u32_e32 v188, 0x17d28, v205
	v_add_u32_e32 v190, 0x17da8, v205
	v_add_u32_e32 v206, 0x17d40, v205
	v_add_u32_e32 v210, 0x17dc0, v205
	v_add_u32_e32 v212, 0x17d48, v205
	v_add_u32_e32 v221, 0x17dc8, v205
	ds_read2_b32 v[180:181], v180 offset1:1
	ds_read2_b32 v[182:183], v182 offset1:1
	ds_read2_b32 v[184:185], v184 offset1:1
	ds_read2_b32 v[186:187], v186 offset1:1
	ds_read2_b32 v[188:189], v188 offset1:1
	ds_read2_b32 v[190:191], v190 offset1:1
	ds_read2_b32 v[206:207], v206 offset1:1
	ds_read2_b32 v[210:211], v210 offset1:1
	ds_read2_b32 v[212:213], v212 offset1:1
	ds_read2_b32 v[224:225], v221 offset1:1
	v_add_u32_e32 v221, 0x17d60, v205
	v_add_u32_e32 v223, 0x17de0, v205
	ds_read2_b32 v[226:227], v221 offset1:1
	ds_read2_b32 v[228:229], v223 offset1:1
	v_add_u32_e32 v221, 0x17d68, v205
	v_add_u32_e32 v205, 0x17de8, v205
	ds_read2_b32 v[230:231], v221 offset1:1
	s_waitcnt lgkmcnt(14)
	v_pk_add_f32 v[96:97], v[96:97], v[176:177]
	ds_read2_b32 v[176:177], v205 offset1:1
	s_waitcnt lgkmcnt(3)
	v_pk_add_f32 v[108:109], v[108:109], v[226:227]
	v_pk_add_f32 v[106:107], v[106:107], v[212:213]
	s_waitcnt lgkmcnt(1)
	v_pk_add_f32 v[110:111], v[110:111], v[230:231]
	v_pk_add_f32 v[104:105], v[104:105], v[206:207]
	v_pk_add_f32 v[102:103], v[102:103], v[188:189]
	v_pk_add_f32 v[100:101], v[100:101], v[184:185]
	v_pk_add_f32 v[98:99], v[98:99], v[180:181]
	s_waitcnt lgkmcnt(0)
	v_pk_add_f32 v[94:95], v[94:95], v[176:177]
	v_pk_add_f32 v[92:93], v[92:93], v[228:229]
	v_pk_add_f32 v[90:91], v[90:91], v[224:225]
	v_pk_add_f32 v[88:89], v[88:89], v[210:211]
	v_pk_add_f32 v[86:87], v[86:87], v[190:191]
	v_pk_add_f32 v[84:85], v[84:85], v[186:187]
	v_pk_add_f32 v[82:83], v[82:83], v[182:183]
	v_pk_add_f32 v[80:81], v[80:81], v[178:179]
	s_nop 0

.Latt_a_bar:
	s_waitcnt lgkmcnt(0)
	s_barrier
	s_nop 9
	v_exp_f32_e32 v224, v96
	v_exp_f32_e32 v225, v97
	v_exp_f32_e32 v176, v80
	v_exp_f32_e32 v177, v81
	v_exp_f32_e32 v226, v98
	v_exp_f32_e32 v227, v99
	v_exp_f32_e32 v178, v82
	v_exp_f32_e32 v179, v83
	v_exp_f32_e32 v228, v100
	v_exp_f32_e32 v229, v101
	v_exp_f32_e32 v180, v84
	v_exp_f32_e32 v181, v85
	v_exp_f32_e32 v230, v102
	v_exp_f32_e32 v231, v103
	v_exp_f32_e32 v182, v86
	v_exp_f32_e32 v183, v87
	v_exp_f32_e32 v248, v104
	v_exp_f32_e32 v249, v105
	v_exp_f32_e32 v184, v88
	v_exp_f32_e32 v185, v89
	v_exp_f32_e32 v250, v106
	v_exp_f32_e32 v251, v107
	v_exp_f32_e32 v186, v90
	v_exp_f32_e32 v187, v91
	v_exp_f32_e32 v210, v108
	v_exp_f32_e32 v211, v109
	v_exp_f32_e32 v188, v92
	v_exp_f32_e32 v189, v93
	v_exp_f32_e32 v212, v110
	v_exp_f32_e32 v213, v111
	v_exp_f32_e32 v190, v94
	v_exp_f32_e32 v191, v95
	v_pk_add_f32 v[204:205], v[224:225], v[226:227]
	v_pk_add_f32 v[206:207], v[210:211], v[212:213]
	v_pk_add_f32 v[232:233], v[182:183], v[184:185]
	v_pk_add_f32 v[204:205], v[204:205], v[228:229]
	v_pk_add_f32 v[206:207], v[206:207], v[176:177]
	v_pk_add_f32 v[232:233], v[232:233], v[186:187]
	v_pk_add_f32 v[204:205], v[204:205], v[230:231]
	v_pk_add_f32 v[206:207], v[206:207], v[178:179]
	v_pk_add_f32 v[232:233], v[232:233], v[188:189]
	v_pk_add_f32 v[204:205], v[204:205], v[248:249]
	v_pk_add_f32 v[206:207], v[206:207], v[180:181]
	v_pk_add_f32 v[232:233], v[232:233], v[190:191]
	v_pk_add_f32 v[204:205], v[204:205], v[250:251]
	s_nop 0
	v_pk_add_f32 v[204:205], v[204:205], v[206:207]
	s_nop 0
	v_pk_add_f32 v[204:205], v[204:205], v[232:233]
	s_nop 0
	v_add_f32_e32 v204, v204, v205
	v_cmp_nge_f32_e32 vcc, 0x43800000, v204
	s_cbranch_vccnz .Latt_a_rare
	v_cvt_pk_bf16_f32 v80, v224, v225
	v_cvt_pk_bf16_f32 v81, v226, v227
	v_cvt_pk_bf16_f32 v82, v228, v229
	v_cvt_pk_bf16_f32 v83, v230, v231
	v_cvt_pk_bf16_f32 v84, v248, v249
	v_cvt_pk_bf16_f32 v85, v250, v251
	v_cvt_pk_bf16_f32 v86, v210, v211
	v_cvt_pk_bf16_f32 v87, v212, v213
	v_cvt_pk_bf16_f32 v88, v176, v177
	v_cvt_pk_bf16_f32 v89, v178, v179
	v_cvt_pk_bf16_f32 v90, v180, v181
	v_cvt_pk_bf16_f32 v91, v182, v183
	v_cvt_pk_bf16_f32 v92, v184, v185
	v_cvt_pk_bf16_f32 v93, v186, v187
	v_cvt_pk_bf16_f32 v94, v188, v189
	v_cvt_pk_bf16_f32 v95, v190, v191
	v_add_f32_e32 v172, v172, v204

.Latt_b_rare:
	v_max_f32_e32 v176, v96, v80
	v_max3_f32 v177, v81, v98, v82
	v_max3_f32 v176, v176, v97, v99
	v_max3_f32 v177, v177, v100, v84
	v_max3_f32 v176, v176, v83, v101
	v_max3_f32 v177, v177, v102, v86
	v_max3_f32 v176, v176, v85, v103
	v_max3_f32 v177, v177, v104, v88
	v_max3_f32 v176, v176, v87, v105
	v_max3_f32 v177, v177, v106, v90
	v_max3_f32 v176, v176, v89, v107
	v_max3_f32 v177, v177, v108, v92
	v_max3_f32 v176, v176, v91, v109
	v_max3_f32 v177, v177, v110, v94
	v_max3_f32 v176, v176, v93, v111
	v_max3_f32 v176, v176, v95, v177
	v_mov_b32_e32 v177, v176
	s_nop 1
	v_permlane32_swap_b32_e32 v176, v177
	v_max_f32_e32 v176, v176, v177
	v_cmp_lt_f32_e32 vcc, 0x41000000, v176
	s_cbranch_vccz .Latt_b_exp
	v_max_f32_e32 v64, v176, v176
	v_max_f32_e32 v66, 0, v64
	v_exp_f32_e64 v176, -v66
	v_add_f32_e32 v173, v173, v66
	v_xor_b32_e32 v64, 0x80000000, v173
	v_pk_add_f32 v[96:97], v[96:97], v[66:67] op_sel_hi:[1,0] neg_lo:[0,1] neg_hi:[0,1]
	v_pk_add_f32 v[80:81], v[80:81], v[66:67] op_sel_hi:[1,0] neg_lo:[0,1] neg_hi:[0,1]
	v_pk_add_f32 v[98:99], v[98:99], v[66:67] op_sel_hi:[1,0] neg_lo:[0,1] neg_hi:[0,1]
	v_pk_add_f32 v[82:83], v[82:83], v[66:67] op_sel_hi:[1,0] neg_lo:[0,1] neg_hi:[0,1]
	v_pk_add_f32 v[100:101], v[100:101], v[66:67] op_sel_hi:[1,0] neg_lo:[0,1] neg_hi:[0,1]
	v_pk_add_f32 v[84:85], v[84:85], v[66:67] op_sel_hi:[1,0] neg_lo:[0,1] neg_hi:[0,1]
	v_pk_add_f32 v[102:103], v[102:103], v[66:67] op_sel_hi:[1,0] neg_lo:[0,1] neg_hi:[0,1]
	v_pk_add_f32 v[86:87], v[86:87], v[66:67] op_sel_hi:[1,0] neg_lo:[0,1] neg_hi:[0,1]
	v_pk_add_f32 v[104:105], v[104:105], v[66:67] op_sel_hi:[1,0] neg_lo:[0,1] neg_hi:[0,1]
	v_pk_add_f32 v[88:89], v[88:89], v[66:67] op_sel_hi:[1,0] neg_lo:[0,1] neg_hi:[0,1]
	v_pk_add_f32 v[106:107], v[106:107], v[66:67] op_sel_hi:[1,0] neg_lo:[0,1] neg_hi:[0,1]
	v_pk_add_f32 v[90:91], v[90:91], v[66:67] op_sel_hi:[1,0] neg_lo:[0,1] neg_hi:[0,1]
	v_pk_add_f32 v[108:109], v[108:109], v[66:67] op_sel_hi:[1,0] neg_lo:[0,1] neg_hi:[0,1]
	v_pk_add_f32 v[92:93], v[92:93], v[66:67] op_sel_hi:[1,0] neg_lo:[0,1] neg_hi:[0,1]
	v_pk_add_f32 v[110:111], v[110:111], v[66:67] op_sel_hi:[1,0] neg_lo:[0,1] neg_hi:[0,1]
	v_pk_add_f32 v[94:95], v[94:95], v[66:67] op_sel_hi:[1,0] neg_lo:[0,1] neg_hi:[0,1]
	v_mov_b32_e32 v65, v64
	v_mov_b32_e32 v66, v64
	v_mov_b32_e32 v67, v64
	v_mov_b32_e32 v68, v64
	v_mov_b32_e32 v69, v64
	v_mov_b32_e32 v70, v64
	v_mov_b32_e32 v71, v64
	v_mov_b32_e32 v72, v64
	v_mov_b32_e32 v73, v64
	v_mov_b32_e32 v74, v64
	v_mov_b32_e32 v75, v64
	v_mov_b32_e32 v76, v64
	v_mov_b32_e32 v77, v64
	v_mov_b32_e32 v78, v64
	v_mov_b32_e32 v79, v64
	v_pk_mul_f32 v[46:47], v[46:47], v[176:177] op_sel_hi:[1,0]
	v_pk_mul_f32 v[44:45], v[44:45], v[176:177] op_sel_hi:[1,0]
	v_pk_mul_f32 v[42:43], v[42:43], v[176:177] op_sel_hi:[1,0]
	v_pk_mul_f32 v[40:41], v[40:41], v[176:177] op_sel_hi:[1,0]
	v_pk_mul_f32 v[38:39], v[38:39], v[176:177] op_sel_hi:[1,0]
	v_pk_mul_f32 v[36:37], v[36:37], v[176:177] op_sel_hi:[1,0]
	v_pk_mul_f32 v[34:35], v[34:35], v[176:177] op_sel_hi:[1,0]
	v_pk_mul_f32 v[32:33], v[32:33], v[176:177] op_sel_hi:[1,0]
	v_pk_mul_f32 v[30:31], v[30:31], v[176:177] op_sel_hi:[1,0]
	v_pk_mul_f32 v[28:29], v[28:29], v[176:177] op_sel_hi:[1,0]
	v_pk_mul_f32 v[26:27], v[26:27], v[176:177] op_sel_hi:[1,0]
	v_pk_mul_f32 v[24:25], v[24:25], v[176:177] op_sel_hi:[1,0]
	v_pk_mul_f32 v[22:23], v[22:23], v[176:177] op_sel_hi:[1,0]
	v_pk_mul_f32 v[20:21], v[20:21], v[176:177] op_sel_hi:[1,0]
	v_pk_mul_f32 v[18:19], v[18:19], v[176:177] op_sel_hi:[1,0]
	v_pk_mul_f32 v[16:17], v[16:17], v[176:177] op_sel_hi:[1,0]
	v_pk_mul_f32 v[14:15], v[14:15], v[176:177] op_sel_hi:[1,0]
	v_pk_mul_f32 v[12:13], v[12:13], v[176:177] op_sel_hi:[1,0]
	v_pk_mul_f32 v[10:11], v[10:11], v[176:177] op_sel_hi:[1,0]
	v_pk_mul_f32 v[8:9], v[8:9], v[176:177] op_sel_hi:[1,0]
	v_pk_mul_f32 v[6:7], v[6:7], v[176:177] op_sel_hi:[1,0]
	v_pk_mul_f32 v[4:5], v[4:5], v[176:177] op_sel_hi:[1,0]
	v_pk_mul_f32 v[2:3], v[2:3], v[176:177] op_sel_hi:[1,0]
	v_pk_mul_f32 v[0:1], v[0:1], v[176:177] op_sel_hi:[1,0]
	v_pk_mul_f32 v[62:63], v[62:63], v[176:177] op_sel_hi:[1,0]
	v_pk_mul_f32 v[60:61], v[60:61], v[176:177] op_sel_hi:[1,0]
	v_pk_mul_f32 v[58:59], v[58:59], v[176:177] op_sel_hi:[1,0]
	v_pk_mul_f32 v[56:57], v[56:57], v[176:177] op_sel_hi:[1,0]
	v_pk_mul_f32 v[54:55], v[54:55], v[176:177] op_sel_hi:[1,0]
	v_pk_mul_f32 v[52:53], v[52:53], v[176:177] op_sel_hi:[1,0]
	v_pk_mul_f32 v[50:51], v[50:51], v[176:177] op_sel_hi:[1,0]
	v_pk_mul_f32 v[48:49], v[48:49], v[176:177] op_sel_hi:[1,0]
	v_mul_f32_e32 v172, v172, v176
.Latt_b_exp:
	v_exp_f32_e32 v96, v96
	v_exp_f32_e32 v97, v97
	v_exp_f32_e32 v176, v80
	v_exp_f32_e32 v177, v81
	v_exp_f32_e32 v98, v98
	v_exp_f32_e32 v99, v99
	v_exp_f32_e32 v178, v82
	v_exp_f32_e32 v179, v83
	v_exp_f32_e32 v100, v100
	v_exp_f32_e32 v101, v101
	v_exp_f32_e32 v180, v84
	v_exp_f32_e32 v181, v85
	v_exp_f32_e32 v102, v102
	v_exp_f32_e32 v103, v103
	v_exp_f32_e32 v182, v86
	v_exp_f32_e32 v183, v87
	v_exp_f32_e32 v104, v104
	v_exp_f32_e32 v105, v105
	v_exp_f32_e32 v184, v88
	v_exp_f32_e32 v185, v89
	v_exp_f32_e32 v106, v106
	v_exp_f32_e32 v107, v107
	v_exp_f32_e32 v186, v90
	v_exp_f32_e32 v187, v91
	v_exp_f32_e32 v108, v108
	v_exp_f32_e32 v109, v109
	v_exp_f32_e32 v188, v92
	v_exp_f32_e32 v189, v93
	v_exp_f32_e32 v110, v110
	v_exp_f32_e32 v111, v111
	v_exp_f32_e32 v190, v94
	v_exp_f32_e32 v191, v95
	v_cvt_pk_bf16_f32 v80, v96, v97
	v_cvt_pk_bf16_f32 v81, v98, v99
	v_cvt_pk_bf16_f32 v82, v100, v101
	v_cvt_pk_bf16_f32 v83, v102, v103
	v_cvt_pk_bf16_f32 v84, v104, v105
	v_cvt_pk_bf16_f32 v85, v106, v107
	v_cvt_pk_bf16_f32 v86, v108, v109
	v_cvt_pk_bf16_f32 v87, v110, v111
	v_cvt_pk_bf16_f32 v88, v176, v177
	v_cvt_pk_bf16_f32 v89, v178, v179
	v_cvt_pk_bf16_f32 v90, v180, v181
	v_cvt_pk_bf16_f32 v91, v182, v183
	v_cvt_pk_bf16_f32 v92, v184, v185
	v_cvt_pk_bf16_f32 v93, v186, v187
	v_cvt_pk_bf16_f32 v94, v188, v189
	v_cvt_pk_bf16_f32 v95, v190, v191
	v_pk_add_f32 v[96:97], v[96:97], v[100:101]
	v_pk_add_f32 v[98:99], v[98:99], v[102:103]
	v_pk_add_f32 v[176:177], v[176:177], v[180:181]
	v_pk_add_f32 v[178:179], v[178:179], v[182:183]
	v_pk_add_f32 v[96:97], v[96:97], v[104:105]
	v_pk_add_f32 v[98:99], v[98:99], v[106:107]
	v_pk_add_f32 v[176:177], v[176:177], v[184:185]
	v_pk_add_f32 v[178:179], v[178:179], v[186:187]
	v_pk_add_f32 v[96:97], v[96:97], v[108:109]
	v_pk_add_f32 v[98:99], v[98:99], v[110:111]
	v_pk_add_f32 v[176:177], v[176:177], v[188:189]
	v_pk_add_f32 v[178:179], v[178:179], v[190:191]
	v_pk_add_f32 v[96:97], v[96:97], v[98:99]
	v_pk_add_f32 v[176:177], v[176:177], v[178:179]
	s_nop 0
	v_pk_add_f32 v[96:97], v[96:97], v[176:177]
	s_nop 0
	v_add_f32_e32 v96, v96, v97
	v_add_f32_e32 v172, v172, v96
	s_branch .Latt_b_smdone
